# plus: token-parallel SwiGLU epilogue in the FFN up GEMM
# speedup vs baseline: 1.0390x; 1.0077x over previous
; #define LAS __attribute__((address_space(3)))
; __device__ __forceinline__ unsigned pk2(float lo, float hi) { unsigned r; asm("v_cvt_pk_bf16_f32 %0, %1, %2" : "=v"(r) : "v"(lo), "v"(hi)); return r; }
; __device__ __forceinline__ float silu_f(float x) { return x * sigmoid_f(x); }
;     __device__ __forceinline__ void operator()(const f32x4 (&acc)[2][2][4][2], const pg8::Unit& u, int wr, int wc, int fr, int fq) const {
;         asm volatile("" : "+v"(fr), "+v"(fq));
;         const int row0 = u.pm * 256 + wr * 64 + fr, col0 = u.pn * 128 + wc * 32 + 8 * fq;
;         const LAS float* sp = side + ui * 512; ++ui;
;         const LAS float* bp = sp + 256 + wc * 32 + 8 * fq;
;         const f32x4 c10 = *(const LAS f32x4*)bp, c11 = *(const LAS f32x4*)(bp + 4), c30 = *(const LAS f32x4*)(bp + 128), c31 = *(const LAS f32x4*)(bp + 128 + 4);
; #pragma unroll
;         for (int ai = 0; ai < 2; ++ai)
; #pragma unroll
;             for (int m = 0; m < 4; ++m) {
;                 const int row = row0 + ai * 128 + m * 16; const float rs = sp[ai * 128 + wr * 64 + m * 16 + fr];
;                 const f32x4 a0 = acc[ai][0][m][0] * rs + c10, a1 = acc[ai][0][m][1] * rs + c11, b0 = acc[ai][1][m][0] * rs + c30, b1 = acc[ai][1][m][1] * rs + c31;
;                 u32x4 w;
;                 w.x = pk2(silu_f(a0[0]) * b0[0], silu_f(a0[1]) * b0[1]); w.y = pk2(silu_f(a0[2]) * b0[2], silu_f(a0[3]) * b0[3]);
;                 w.z = pk2(silu_f(a1[0]) * b1[0], silu_f(a1[1]) * b1[1]); w.w = pk2(silu_f(a1[2]) * b1[2], silu_f(a1[3]) * b1[3]);
;                 *(u32x4*)(G + (size_t)row * PW + col0) = w;
.LBB0_354:
	s_lshl_b32 s3, s16, 7
	v_mov_b32_e32 v48, v163
	v_mov_b32_e32 v159, v162
	s_or_b32 s3, s3, s40
	s_lshl_b32 s2, s18, 8
	v_lshl_add_u32 v158, v48, 3, s3
	s_lshl_b32 s3, s17, 11
	s_add_i32 s3, s3, 0
	s_add_i32 s2, s2, s39
	s_add_i32 s3, s3, 0x20000
	s_lshl_b32 s9, s40, 2
	v_add_u32_e32 v166, s2, v159
	s_lshl_b32 s2, s39, 2
	s_add_i32 s9, s3, s9
	s_add_i32 s3, s3, s2
	v_lshl_add_u32 v48, v48, 5, s9
	v_lshl_add_u32 v167, v159, 2, s3
	ds_read_b128 v[60:63], v48 offset:1024
	ds_read_b128 v[56:59], v48 offset:1040
	ds_read_b128 v[52:55], v48 offset:1536
	ds_read_b128 v[48:51], v48 offset:1552
	ds_read2_b32 v[160:161], v167 offset1:16
	v_ashrrev_i32_e32 v159, 31, v158
	s_mov_b64 s[16:17], -1
	s_andn2_b64 vcc, exec, s[4:5]
	ds_read_b32 v168, v167 offset:0
	ds_read_b32 v170, v167 offset:64
	ds_read_b32 v172, v167 offset:128
	ds_read_b32 v174, v167 offset:192
	ds_read_b32 v176, v167 offset:512
	ds_read_b32 v178, v167 offset:576
	ds_read_b32 v180, v167 offset:640
	ds_read_b32 v182, v167 offset:704
	v_mov_b32_e32 v192, 0xbfb8aa3b
	v_mov_b32_e32 v193, 0xbfb8aa3b
	s_movk_i32 s2, 0x1600
	v_mul_lo_u32 v184, v166, s2
	v_lshl_add_u32 v184, v158, 1, v184
	v_add_u32_e32 v185, 0x16000, v184
	v_add_u32_e32 v186, 0x2c000, v184
	v_add_u32_e32 v187, 0x42000, v184
	v_add_u32_e32 v188, 0xb0000, v184
	v_add_u32_e32 v189, 0xc6000, v184
	v_add_u32_e32 v190, 0xdc000, v184
	v_add_u32_e32 v191, 0xf2000, v184
	s_waitcnt lgkmcnt(0)
	v_pk_fma_f32 v[140:141], v[140:141], v[168:169], v[60:61] op_sel_hi:[1,0,1]
	v_pk_fma_f32 v[142:143], v[142:143], v[168:169], v[62:63] op_sel_hi:[1,0,1]
	v_pk_fma_f32 v[136:137], v[136:137], v[168:169], v[56:57] op_sel_hi:[1,0,1]
	v_pk_fma_f32 v[138:139], v[138:139], v[168:169], v[58:59] op_sel_hi:[1,0,1]
	v_pk_fma_f32 v[132:133], v[132:133], v[168:169], v[52:53] op_sel_hi:[1,0,1]
	v_pk_fma_f32 v[134:135], v[134:135], v[168:169], v[54:55] op_sel_hi:[1,0,1]
	v_pk_fma_f32 v[128:129], v[128:129], v[168:169], v[48:49] op_sel_hi:[1,0,1]
	v_pk_fma_f32 v[130:131], v[130:131], v[168:169], v[50:51] op_sel_hi:[1,0,1]
	v_pk_fma_f32 v[124:125], v[124:125], v[170:171], v[60:61] op_sel_hi:[1,0,1]
	v_pk_fma_f32 v[126:127], v[126:127], v[170:171], v[62:63] op_sel_hi:[1,0,1]
	v_pk_fma_f32 v[120:121], v[120:121], v[170:171], v[56:57] op_sel_hi:[1,0,1]
	v_pk_fma_f32 v[122:123], v[122:123], v[170:171], v[58:59] op_sel_hi:[1,0,1]
	v_pk_fma_f32 v[116:117], v[116:117], v[170:171], v[52:53] op_sel_hi:[1,0,1]
	v_pk_fma_f32 v[118:119], v[118:119], v[170:171], v[54:55] op_sel_hi:[1,0,1]
	v_pk_fma_f32 v[112:113], v[112:113], v[170:171], v[48:49] op_sel_hi:[1,0,1]
	v_pk_fma_f32 v[114:115], v[114:115], v[170:171], v[50:51] op_sel_hi:[1,0,1]
	v_pk_mul_f32 v[194:195], v[192:193], v[140:141]
	v_pk_mul_f32 v[196:197], v[192:193], v[142:143]
	v_pk_mul_f32 v[198:199], v[192:193], v[136:137]
	v_pk_mul_f32 v[200:201], v[192:193], v[138:139]
	v_pk_mul_f32 v[202:203], v[192:193], v[124:125]
	v_pk_mul_f32 v[204:205], v[192:193], v[126:127]
	v_pk_mul_f32 v[206:207], v[192:193], v[120:121]
	v_pk_mul_f32 v[208:209], v[192:193], v[122:123]
	v_exp_f32_e32 v194, v194
	v_exp_f32_e32 v195, v195
	v_exp_f32_e32 v196, v196
	v_exp_f32_e32 v197, v197
	v_exp_f32_e32 v198, v198
	v_exp_f32_e32 v199, v199
	v_exp_f32_e32 v200, v200
	v_exp_f32_e32 v201, v201
	v_exp_f32_e32 v202, v202
	v_exp_f32_e32 v203, v203
	v_exp_f32_e32 v204, v204
	v_exp_f32_e32 v205, v205
	v_exp_f32_e32 v206, v206
	v_exp_f32_e32 v207, v207
	v_exp_f32_e32 v208, v208
	v_exp_f32_e32 v209, v209
	v_pk_add_f32 v[194:195], v[194:195], 1.0 op_sel_hi:[1,0]
	v_pk_add_f32 v[196:197], v[196:197], 1.0 op_sel_hi:[1,0]
	v_pk_add_f32 v[198:199], v[198:199], 1.0 op_sel_hi:[1,0]
	v_pk_add_f32 v[200:201], v[200:201], 1.0 op_sel_hi:[1,0]
	v_pk_add_f32 v[202:203], v[202:203], 1.0 op_sel_hi:[1,0]
	v_pk_add_f32 v[204:205], v[204:205], 1.0 op_sel_hi:[1,0]
	v_pk_add_f32 v[206:207], v[206:207], 1.0 op_sel_hi:[1,0]
	v_pk_add_f32 v[208:209], v[208:209], 1.0 op_sel_hi:[1,0]
	v_rcp_f32_e32 v194, v194
	v_rcp_f32_e32 v195, v195
	v_rcp_f32_e32 v196, v196
	v_rcp_f32_e32 v197, v197
	v_rcp_f32_e32 v198, v198
	v_rcp_f32_e32 v199, v199
	v_rcp_f32_e32 v200, v200
	v_rcp_f32_e32 v201, v201
	v_rcp_f32_e32 v202, v202
	v_rcp_f32_e32 v203, v203
	v_rcp_f32_e32 v204, v204
	v_rcp_f32_e32 v205, v205
	v_rcp_f32_e32 v206, v206
	v_rcp_f32_e32 v207, v207
	v_rcp_f32_e32 v208, v208
	v_rcp_f32_e32 v209, v209
	s_nop 0
	v_pk_mul_f32 v[194:195], v[140:141], v[194:195]
	v_pk_mul_f32 v[196:197], v[142:143], v[196:197]
	v_pk_mul_f32 v[198:199], v[136:137], v[198:199]
	v_pk_mul_f32 v[200:201], v[138:139], v[200:201]
	v_pk_mul_f32 v[202:203], v[124:125], v[202:203]
	v_pk_mul_f32 v[204:205], v[126:127], v[204:205]
	v_pk_mul_f32 v[206:207], v[120:121], v[206:207]
	v_pk_mul_f32 v[208:209], v[122:123], v[208:209]
	v_pk_mul_f32 v[194:195], v[132:133], v[194:195]
	v_pk_mul_f32 v[196:197], v[134:135], v[196:197]
	v_pk_mul_f32 v[198:199], v[128:129], v[198:199]
	v_pk_mul_f32 v[200:201], v[130:131], v[200:201]
	v_pk_mul_f32 v[202:203], v[116:117], v[202:203]
	v_pk_mul_f32 v[204:205], v[118:119], v[204:205]
	v_pk_mul_f32 v[206:207], v[112:113], v[206:207]
	v_pk_mul_f32 v[208:209], v[114:115], v[208:209]
	v_cvt_pk_bf16_f32 v228, v194, v195
	v_cvt_pk_bf16_f32 v229, v196, v197
	v_cvt_pk_bf16_f32 v230, v198, v199
	v_cvt_pk_bf16_f32 v231, v200, v201
	v_cvt_pk_bf16_f32 v232, v202, v203
	v_cvt_pk_bf16_f32 v233, v204, v205
	v_cvt_pk_bf16_f32 v234, v206, v207
	v_cvt_pk_bf16_f32 v235, v208, v209
	global_store_dwordx4 v184, v[228:231], s[70:71]
	global_store_dwordx4 v185, v[232:235], s[70:71]
	v_pk_fma_f32 v[108:109], v[108:109], v[172:173], v[60:61] op_sel_hi:[1,0,1]
; #define LAS __attribute__((address_space(3)))
; __device__ __forceinline__ unsigned pk2(float lo, float hi) { unsigned r; asm("v_cvt_pk_bf16_f32 %0, %1, %2" : "=v"(r) : "v"(lo), "v"(hi)); return r; }
; __device__ __forceinline__ float silu_f(float x) { return x * sigmoid_f(x); }
;     __device__ __forceinline__ void operator()(const f32x4 (&acc)[2][2][4][2], const pg8::Unit& u, int wr, int wc, int fr, int fq) const {
;     ...
;         const f32x4 c10 = *(const LAS f32x4*)bp, c11 = *(const LAS f32x4*)(bp + 4), c30 = *(const LAS f32x4*)(bp + 128), c31 = *(const LAS f32x4*)(bp + 128 + 4);
; #pragma unroll
;         for (int ai = 0; ai < 2; ++ai)
; #pragma unroll
;             for (int m = 0; m < 4; ++m) {
;                 const int row = row0 + ai * 128 + m * 16; const float rs = sp[ai * 128 + wr * 64 + m * 16 + fr];
;                 const f32x4 a0 = acc[ai][0][m][0] * rs + c10, a1 = acc[ai][0][m][1] * rs + c11, b0 = acc[ai][1][m][0] * rs + c30, b1 = acc[ai][1][m][1] * rs + c31;
;                 u32x4 w;
;                 w.x = pk2(silu_f(a0[0]) * b0[0], silu_f(a0[1]) * b0[1]); w.y = pk2(silu_f(a0[2]) * b0[2], silu_f(a0[3]) * b0[3]);
;                 w.z = pk2(silu_f(a1[0]) * b1[0], silu_f(a1[1]) * b1[1]); w.w = pk2(silu_f(a1[2]) * b1[2], silu_f(a1[3]) * b1[3]);
;                 *(u32x4*)(G + (size_t)row * PW + col0) = w;
	v_pk_fma_f32 v[110:111], v[110:111], v[172:173], v[62:63] op_sel_hi:[1,0,1]
	v_pk_fma_f32 v[104:105], v[104:105], v[172:173], v[56:57] op_sel_hi:[1,0,1]
	v_pk_fma_f32 v[106:107], v[106:107], v[172:173], v[58:59] op_sel_hi:[1,0,1]
	v_pk_fma_f32 v[100:101], v[100:101], v[172:173], v[52:53] op_sel_hi:[1,0,1]
	v_pk_fma_f32 v[102:103], v[102:103], v[172:173], v[54:55] op_sel_hi:[1,0,1]
	v_pk_fma_f32 v[96:97], v[96:97], v[172:173], v[48:49] op_sel_hi:[1,0,1]
	v_pk_fma_f32 v[98:99], v[98:99], v[172:173], v[50:51] op_sel_hi:[1,0,1]
	v_pk_fma_f32 v[92:93], v[92:93], v[174:175], v[60:61] op_sel_hi:[1,0,1]
	v_pk_fma_f32 v[94:95], v[94:95], v[174:175], v[62:63] op_sel_hi:[1,0,1]
	v_pk_fma_f32 v[88:89], v[88:89], v[174:175], v[56:57] op_sel_hi:[1,0,1]
	v_pk_fma_f32 v[90:91], v[90:91], v[174:175], v[58:59] op_sel_hi:[1,0,1]
	v_pk_fma_f32 v[84:85], v[84:85], v[174:175], v[52:53] op_sel_hi:[1,0,1]
	v_pk_fma_f32 v[86:87], v[86:87], v[174:175], v[54:55] op_sel_hi:[1,0,1]
	v_pk_fma_f32 v[80:81], v[80:81], v[174:175], v[48:49] op_sel_hi:[1,0,1]
	v_pk_fma_f32 v[82:83], v[82:83], v[174:175], v[50:51] op_sel_hi:[1,0,1]
	v_pk_mul_f32 v[194:195], v[192:193], v[108:109]
	v_pk_mul_f32 v[196:197], v[192:193], v[110:111]
	v_pk_mul_f32 v[198:199], v[192:193], v[104:105]
	v_pk_mul_f32 v[200:201], v[192:193], v[106:107]
	v_pk_mul_f32 v[202:203], v[192:193], v[92:93]
	v_pk_mul_f32 v[204:205], v[192:193], v[94:95]
	v_pk_mul_f32 v[206:207], v[192:193], v[88:89]
	v_pk_mul_f32 v[208:209], v[192:193], v[90:91]
	v_exp_f32_e32 v194, v194
	v_exp_f32_e32 v195, v195
	v_exp_f32_e32 v196, v196
	v_exp_f32_e32 v197, v197
	v_exp_f32_e32 v198, v198
	v_exp_f32_e32 v199, v199
	v_exp_f32_e32 v200, v200
	v_exp_f32_e32 v201, v201
	v_exp_f32_e32 v202, v202
	v_exp_f32_e32 v203, v203
	v_exp_f32_e32 v204, v204
	v_exp_f32_e32 v205, v205
	v_exp_f32_e32 v206, v206
	v_exp_f32_e32 v207, v207
	v_exp_f32_e32 v208, v208
	v_exp_f32_e32 v209, v209
	v_pk_add_f32 v[194:195], v[194:195], 1.0 op_sel_hi:[1,0]
	v_pk_add_f32 v[196:197], v[196:197], 1.0 op_sel_hi:[1,0]
	v_pk_add_f32 v[198:199], v[198:199], 1.0 op_sel_hi:[1,0]
	v_pk_add_f32 v[200:201], v[200:201], 1.0 op_sel_hi:[1,0]
	v_pk_add_f32 v[202:203], v[202:203], 1.0 op_sel_hi:[1,0]
	v_pk_add_f32 v[204:205], v[204:205], 1.0 op_sel_hi:[1,0]
	v_pk_add_f32 v[206:207], v[206:207], 1.0 op_sel_hi:[1,0]
	v_pk_add_f32 v[208:209], v[208:209], 1.0 op_sel_hi:[1,0]
	v_rcp_f32_e32 v194, v194
	v_rcp_f32_e32 v195, v195
	v_rcp_f32_e32 v196, v196
	v_rcp_f32_e32 v197, v197
	v_rcp_f32_e32 v198, v198
	v_rcp_f32_e32 v199, v199
	v_rcp_f32_e32 v200, v200
	v_rcp_f32_e32 v201, v201
	v_rcp_f32_e32 v202, v202
	v_rcp_f32_e32 v203, v203
	v_rcp_f32_e32 v204, v204
	v_rcp_f32_e32 v205, v205
	v_rcp_f32_e32 v206, v206
	v_rcp_f32_e32 v207, v207
	v_rcp_f32_e32 v208, v208
	v_rcp_f32_e32 v209, v209
	s_nop 0
	v_pk_mul_f32 v[194:195], v[108:109], v[194:195]
	v_pk_mul_f32 v[196:197], v[110:111], v[196:197]
	v_pk_mul_f32 v[198:199], v[104:105], v[198:199]
	v_pk_mul_f32 v[200:201], v[106:107], v[200:201]
	v_pk_mul_f32 v[202:203], v[92:93], v[202:203]
	v_pk_mul_f32 v[204:205], v[94:95], v[204:205]
	v_pk_mul_f32 v[206:207], v[88:89], v[206:207]
	v_pk_mul_f32 v[208:209], v[90:91], v[208:209]
	v_pk_mul_f32 v[194:195], v[100:101], v[194:195]
	v_pk_mul_f32 v[196:197], v[102:103], v[196:197]
	v_pk_mul_f32 v[198:199], v[96:97], v[198:199]
	v_pk_mul_f32 v[200:201], v[98:99], v[200:201]
	v_pk_mul_f32 v[202:203], v[84:85], v[202:203]
	v_pk_mul_f32 v[204:205], v[86:87], v[204:205]
	v_pk_mul_f32 v[206:207], v[80:81], v[206:207]
	v_pk_mul_f32 v[208:209], v[82:83], v[208:209]
	v_cvt_pk_bf16_f32 v236, v194, v195
	v_cvt_pk_bf16_f32 v237, v196, v197
	v_cvt_pk_bf16_f32 v238, v198, v199
	v_cvt_pk_bf16_f32 v239, v200, v201
	v_cvt_pk_bf16_f32 v240, v202, v203
	v_cvt_pk_bf16_f32 v241, v204, v205
	v_cvt_pk_bf16_f32 v242, v206, v207
	v_cvt_pk_bf16_f32 v243, v208, v209
	global_store_dwordx4 v186, v[236:239], s[70:71]
	global_store_dwordx4 v187, v[240:243], s[70:71]
	v_pk_fma_f32 v[76:77], v[76:77], v[176:177], v[60:61] op_sel_hi:[1,0,1]
	v_pk_fma_f32 v[78:79], v[78:79], v[176:177], v[62:63] op_sel_hi:[1,0,1]
	v_pk_fma_f32 v[72:73], v[72:73], v[176:177], v[56:57] op_sel_hi:[1,0,1]
	v_pk_fma_f32 v[74:75], v[74:75], v[176:177], v[58:59] op_sel_hi:[1,0,1]
	v_pk_fma_f32 v[68:69], v[68:69], v[176:177], v[52:53] op_sel_hi:[1,0,1]
	v_pk_fma_f32 v[70:71], v[70:71], v[176:177], v[54:55] op_sel_hi:[1,0,1]
	v_pk_fma_f32 v[64:65], v[64:65], v[176:177], v[48:49] op_sel_hi:[1,0,1]
	v_pk_fma_f32 v[66:67], v[66:67], v[176:177], v[50:51] op_sel_hi:[1,0,1]
	v_pk_fma_f32 v[44:45], v[44:45], v[178:179], v[60:61] op_sel_hi:[1,0,1]
	v_pk_fma_f32 v[46:47], v[46:47], v[178:179], v[62:63] op_sel_hi:[1,0,1]
	v_pk_fma_f32 v[40:41], v[40:41], v[178:179], v[56:57] op_sel_hi:[1,0,1]
	v_pk_fma_f32 v[42:43], v[42:43], v[178:179], v[58:59] op_sel_hi:[1,0,1]
	v_pk_fma_f32 v[36:37], v[36:37], v[178:179], v[52:53] op_sel_hi:[1,0,1]
	v_pk_fma_f32 v[38:39], v[38:39], v[178:179], v[54:55] op_sel_hi:[1,0,1]
	v_pk_fma_f32 v[32:33], v[32:33], v[178:179], v[48:49] op_sel_hi:[1,0,1]
	v_pk_fma_f32 v[34:35], v[34:35], v[178:179], v[50:51] op_sel_hi:[1,0,1]
	v_pk_mul_f32 v[194:195], v[192:193], v[76:77]
	v_pk_mul_f32 v[196:197], v[192:193], v[78:79]
	v_pk_mul_f32 v[198:199], v[192:193], v[72:73]
	v_pk_mul_f32 v[200:201], v[192:193], v[74:75]
	v_pk_mul_f32 v[202:203], v[192:193], v[44:45]
	v_pk_mul_f32 v[204:205], v[192:193], v[46:47]
	v_pk_mul_f32 v[206:207], v[192:193], v[40:41]
	v_pk_mul_f32 v[208:209], v[192:193], v[42:43]
	v_exp_f32_e32 v194, v194
	v_exp_f32_e32 v195, v195
	v_exp_f32_e32 v196, v196
	v_exp_f32_e32 v197, v197
	v_exp_f32_e32 v198, v198
; #define PG8_BAR __builtin_amdgcn_s_barrier()
; #define LAS __attribute__((address_space(3)))
; __device__ __forceinline__ unsigned pk2(float lo, float hi) { unsigned r; asm("v_cvt_pk_bf16_f32 %0, %1, %2" : "=v"(r) : "v"(lo), "v"(hi)); return r; }
; __device__ __forceinline__ float silu_f(float x) { return x * sigmoid_f(x); }
; template <class Epi, class Sched, bool ALIGN_EPI = false, bool SP2 = false>
; __device__ __forceinline__ void gemm_phase(PG8_LAS unsigned char* lds, const Gemm g, const Sched& S, const Epi& E, int tid_in) {
;     ...
;         if constexpr (ALIGN_EPI) { if (wr == 0) PG8_BAR; }
;         if constexpr (!Epi::AFTER_DRAIN) { E(acc, cur, wr, wc, fr, fq); S.done(cur); }
;         if (!has_next) break;
;     __device__ __forceinline__ void operator()(const f32x4 (&acc)[2][2][4][2], const pg8::Unit& u, int wr, int wc, int fr, int fq) const {
;     ...
;         const f32x4 c10 = *(const LAS f32x4*)bp, c11 = *(const LAS f32x4*)(bp + 4), c30 = *(const LAS f32x4*)(bp + 128), c31 = *(const LAS f32x4*)(bp + 128 + 4);
; #pragma unroll
;         for (int ai = 0; ai < 2; ++ai)
; #pragma unroll
;             for (int m = 0; m < 4; ++m) {
;                 const int row = row0 + ai * 128 + m * 16; const float rs = sp[ai * 128 + wr * 64 + m * 16 + fr];
;                 const f32x4 a0 = acc[ai][0][m][0] * rs + c10, a1 = acc[ai][0][m][1] * rs + c11, b0 = acc[ai][1][m][0] * rs + c30, b1 = acc[ai][1][m][1] * rs + c31;
;                 u32x4 w;
;                 w.x = pk2(silu_f(a0[0]) * b0[0], silu_f(a0[1]) * b0[1]); w.y = pk2(silu_f(a0[2]) * b0[2], silu_f(a0[3]) * b0[3]);
;                 w.z = pk2(silu_f(a1[0]) * b1[0], silu_f(a1[1]) * b1[1]); w.w = pk2(silu_f(a1[2]) * b1[2], silu_f(a1[3]) * b1[3]);
;                 *(u32x4*)(G + (size_t)row * PW + col0) = w;
;             }
	v_exp_f32_e32 v199, v199
	v_exp_f32_e32 v200, v200
	v_exp_f32_e32 v201, v201
	v_exp_f32_e32 v202, v202
	v_exp_f32_e32 v203, v203
	v_exp_f32_e32 v204, v204
	v_exp_f32_e32 v205, v205
	v_exp_f32_e32 v206, v206
	v_exp_f32_e32 v207, v207
	v_exp_f32_e32 v208, v208
	v_exp_f32_e32 v209, v209
	v_pk_add_f32 v[194:195], v[194:195], 1.0 op_sel_hi:[1,0]
	v_pk_add_f32 v[196:197], v[196:197], 1.0 op_sel_hi:[1,0]
	v_pk_add_f32 v[198:199], v[198:199], 1.0 op_sel_hi:[1,0]
	v_pk_add_f32 v[200:201], v[200:201], 1.0 op_sel_hi:[1,0]
	v_pk_add_f32 v[202:203], v[202:203], 1.0 op_sel_hi:[1,0]
	v_pk_add_f32 v[204:205], v[204:205], 1.0 op_sel_hi:[1,0]
	v_pk_add_f32 v[206:207], v[206:207], 1.0 op_sel_hi:[1,0]
	v_pk_add_f32 v[208:209], v[208:209], 1.0 op_sel_hi:[1,0]
	v_rcp_f32_e32 v194, v194
	v_rcp_f32_e32 v195, v195
	v_rcp_f32_e32 v196, v196
	v_rcp_f32_e32 v197, v197
	v_rcp_f32_e32 v198, v198
	v_rcp_f32_e32 v199, v199
	v_rcp_f32_e32 v200, v200
	v_rcp_f32_e32 v201, v201
	v_rcp_f32_e32 v202, v202
	v_rcp_f32_e32 v203, v203
	v_rcp_f32_e32 v204, v204
	v_rcp_f32_e32 v205, v205
	v_rcp_f32_e32 v206, v206
	v_rcp_f32_e32 v207, v207
	v_rcp_f32_e32 v208, v208
	v_rcp_f32_e32 v209, v209
	s_nop 0
	v_pk_mul_f32 v[194:195], v[76:77], v[194:195]
	v_pk_mul_f32 v[196:197], v[78:79], v[196:197]
	v_pk_mul_f32 v[198:199], v[72:73], v[198:199]
	v_pk_mul_f32 v[200:201], v[74:75], v[200:201]
	v_pk_mul_f32 v[202:203], v[44:45], v[202:203]
	v_pk_mul_f32 v[204:205], v[46:47], v[204:205]
	v_pk_mul_f32 v[206:207], v[40:41], v[206:207]
	v_pk_mul_f32 v[208:209], v[42:43], v[208:209]
	v_pk_mul_f32 v[194:195], v[68:69], v[194:195]
	v_pk_mul_f32 v[196:197], v[70:71], v[196:197]
	v_pk_mul_f32 v[198:199], v[64:65], v[198:199]
	v_pk_mul_f32 v[200:201], v[66:67], v[200:201]
	v_pk_mul_f32 v[202:203], v[36:37], v[202:203]
	v_pk_mul_f32 v[204:205], v[38:39], v[204:205]
	v_pk_mul_f32 v[206:207], v[32:33], v[206:207]
	v_pk_mul_f32 v[208:209], v[34:35], v[208:209]
	v_cvt_pk_bf16_f32 v244, v194, v195
	v_cvt_pk_bf16_f32 v245, v196, v197
	v_cvt_pk_bf16_f32 v246, v198, v199
	v_cvt_pk_bf16_f32 v247, v200, v201
	v_cvt_pk_bf16_f32 v248, v202, v203
	v_cvt_pk_bf16_f32 v249, v204, v205
	v_cvt_pk_bf16_f32 v250, v206, v207
	v_cvt_pk_bf16_f32 v251, v208, v209
	global_store_dwordx4 v188, v[244:247], s[70:71]
	global_store_dwordx4 v189, v[248:251], s[70:71]
	v_pk_fma_f32 v[28:29], v[28:29], v[180:181], v[60:61] op_sel_hi:[1,0,1]
	v_pk_fma_f32 v[30:31], v[30:31], v[180:181], v[62:63] op_sel_hi:[1,0,1]
	v_pk_fma_f32 v[24:25], v[24:25], v[180:181], v[56:57] op_sel_hi:[1,0,1]
	v_pk_fma_f32 v[26:27], v[26:27], v[180:181], v[58:59] op_sel_hi:[1,0,1]
	v_pk_fma_f32 v[20:21], v[20:21], v[180:181], v[52:53] op_sel_hi:[1,0,1]
	v_pk_fma_f32 v[22:23], v[22:23], v[180:181], v[54:55] op_sel_hi:[1,0,1]
	v_pk_fma_f32 v[16:17], v[16:17], v[180:181], v[48:49] op_sel_hi:[1,0,1]
	v_pk_fma_f32 v[18:19], v[18:19], v[180:181], v[50:51] op_sel_hi:[1,0,1]
	v_pk_fma_f32 v[12:13], v[12:13], v[182:183], v[60:61] op_sel_hi:[1,0,1]
	v_pk_fma_f32 v[14:15], v[14:15], v[182:183], v[62:63] op_sel_hi:[1,0,1]
	v_pk_fma_f32 v[8:9], v[8:9], v[182:183], v[56:57] op_sel_hi:[1,0,1]
	v_pk_fma_f32 v[10:11], v[10:11], v[182:183], v[58:59] op_sel_hi:[1,0,1]
	v_pk_fma_f32 v[4:5], v[4:5], v[182:183], v[52:53] op_sel_hi:[1,0,1]
	v_pk_fma_f32 v[6:7], v[6:7], v[182:183], v[54:55] op_sel_hi:[1,0,1]
	v_pk_fma_f32 v[0:1], v[0:1], v[182:183], v[48:49] op_sel_hi:[1,0,1]
	v_pk_fma_f32 v[2:3], v[2:3], v[182:183], v[50:51] op_sel_hi:[1,0,1]
	v_pk_mul_f32 v[194:195], v[192:193], v[28:29]
	v_pk_mul_f32 v[196:197], v[192:193], v[30:31]
	v_pk_mul_f32 v[198:199], v[192:193], v[24:25]
	v_pk_mul_f32 v[200:201], v[192:193], v[26:27]
	v_pk_mul_f32 v[202:203], v[192:193], v[12:13]
	v_pk_mul_f32 v[204:205], v[192:193], v[14:15]
	v_pk_mul_f32 v[206:207], v[192:193], v[8:9]
	v_pk_mul_f32 v[208:209], v[192:193], v[10:11]
	v_exp_f32_e32 v194, v194
	v_exp_f32_e32 v195, v195
	v_exp_f32_e32 v196, v196
	v_exp_f32_e32 v197, v197
	v_exp_f32_e32 v198, v198
	v_exp_f32_e32 v199, v199
	v_exp_f32_e32 v200, v200
	v_exp_f32_e32 v201, v201
	v_exp_f32_e32 v202, v202
	v_exp_f32_e32 v203, v203
	v_exp_f32_e32 v204, v204
	v_exp_f32_e32 v205, v205
	v_exp_f32_e32 v206, v206
	v_exp_f32_e32 v207, v207
	v_exp_f32_e32 v208, v208
	v_exp_f32_e32 v209, v209
	v_pk_add_f32 v[194:195], v[194:195], 1.0 op_sel_hi:[1,0]
	v_pk_add_f32 v[196:197], v[196:197], 1.0 op_sel_hi:[1,0]
	v_pk_add_f32 v[198:199], v[198:199], 1.0 op_sel_hi:[1,0]
	v_pk_add_f32 v[200:201], v[200:201], 1.0 op_sel_hi:[1,0]
	v_pk_add_f32 v[202:203], v[202:203], 1.0 op_sel_hi:[1,0]
	v_pk_add_f32 v[204:205], v[204:205], 1.0 op_sel_hi:[1,0]
	v_pk_add_f32 v[206:207], v[206:207], 1.0 op_sel_hi:[1,0]
	v_pk_add_f32 v[208:209], v[208:209], 1.0 op_sel_hi:[1,0]
	v_rcp_f32_e32 v194, v194
	v_rcp_f32_e32 v195, v195
	v_rcp_f32_e32 v196, v196
	v_rcp_f32_e32 v197, v197
	v_rcp_f32_e32 v198, v198
	v_rcp_f32_e32 v199, v199
	v_rcp_f32_e32 v200, v200
	v_rcp_f32_e32 v201, v201
	v_rcp_f32_e32 v202, v202
	v_rcp_f32_e32 v203, v203
	v_rcp_f32_e32 v204, v204
	v_rcp_f32_e32 v205, v205
	v_rcp_f32_e32 v206, v206
	v_rcp_f32_e32 v207, v207
	v_rcp_f32_e32 v208, v208
	v_rcp_f32_e32 v209, v209
	s_nop 0
	v_pk_mul_f32 v[194:195], v[28:29], v[194:195]
	v_pk_mul_f32 v[196:197], v[30:31], v[196:197]
	v_pk_mul_f32 v[198:199], v[24:25], v[198:199]
	v_pk_mul_f32 v[200:201], v[26:27], v[200:201]
	v_pk_mul_f32 v[202:203], v[12:13], v[202:203]
	v_pk_mul_f32 v[204:205], v[14:15], v[204:205]
	v_pk_mul_f32 v[206:207], v[8:9], v[206:207]
	v_pk_mul_f32 v[208:209], v[10:11], v[208:209]
	v_pk_mul_f32 v[194:195], v[20:21], v[194:195]
	v_pk_mul_f32 v[196:197], v[22:23], v[196:197]
	v_pk_mul_f32 v[198:199], v[16:17], v[198:199]
	v_pk_mul_f32 v[200:201], v[18:19], v[200:201]
	v_pk_mul_f32 v[202:203], v[4:5], v[202:203]
	v_pk_mul_f32 v[204:205], v[6:7], v[204:205]
	v_pk_mul_f32 v[206:207], v[0:1], v[206:207]
	v_pk_mul_f32 v[208:209], v[2:3], v[208:209]
	v_cvt_pk_bf16_f32 v212, v194, v195
	v_cvt_pk_bf16_f32 v213, v196, v197
	v_cvt_pk_bf16_f32 v214, v198, v199
	v_cvt_pk_bf16_f32 v215, v200, v201
	v_cvt_pk_bf16_f32 v216, v202, v203
	v_cvt_pk_bf16_f32 v217, v204, v205
	v_cvt_pk_bf16_f32 v218, v206, v207
	v_cvt_pk_bf16_f32 v219, v208, v209
	global_store_dwordx4 v190, v[212:215], s[70:71]
	global_store_dwordx4 v191, v[216:219], s[70:71]
	s_cbranch_vccnz .LBB0_343
	s_andn2_b64 vcc, exec, s[0:1]
	s_cbranch_vccnz .LBB0_342
	s_barrier
	s_branch .LBB0_342
